# v28 plus LN-fold sums of the up-projection weights computed in the prologue transpose (per k-block partials) with a small fixed-order second pass; fold phase reads only the in-projection weights
# speedup vs baseline: 1.0143x; 1.0143x over previous
.LBB0_215:
	v_readlane_b32 s0, v254, 30
	s_add_i32 s0, s0, 4
	v_readlane_b32 s90, v255, 16
	v_readlane_b32 s94, v255, 18
	v_readlane_b32 s80, v254, 57
	v_readlane_b32 s84, v254, 59
	s_cmp_lt_u32 s0, 11
	v_readlane_b32 s87, v255, 15
	v_readlane_b32 s91, v255, 17
	v_readlane_b32 s95, v255, 19
	v_readlane_b32 s81, v254, 58
	v_readlane_b32 s85, v254, 60
	v_readlane_b32 s50, v254, 61
	v_readlane_b32 s86, v254, 63
	v_readlane_b32 s88, v255, 5
	v_readlane_b32 s89, v255, 6
	v_readlane_b32 s92, v255, 7
	v_readlane_b32 s93, v255, 8
	v_readlane_b32 s96, v255, 9
	v_readlane_b32 s97, v255, 10
	v_readlane_b32 s51, v254, 62
	s_cbranch_scc0 .LBB0_231
	v_readfirstlane_b32 s0, v223
	s_ashr_i32 s0, s0, 6
	v_readlane_b32 s1, v253, 22
	s_add_i32 s0, s0, s1
	v_readlane_b32 s1, v254, 10
	v_readlane_b32 s4, v252, 0
	s_mov_b32 s5, 0xec00
	s_nop 2
	s_cmpk_eq_u32 s4, 0x100
	s_cselect_b32 s1, 8, s1
	s_cselect_b32 s5, 0x3c00, s5
	s_mul_i32 s8, s0, s1
	s_add_i32 s0, s8, s1
	s_min_i32 s4, s0, s5
	s_cmp_ge_i32 s8, s4
	s_cbranch_scc1 .LBB0_231
	v_lshlrev_b32_e32 v0, 3, v135
	v_cmp_eq_u32_e64 s[36:37], 0, v135
	v_lshlrev_b32_e32 v72, 4, v135
	v_mov_b32_e32 v73, v85
	v_lshlrev_b32_e32 v84, 2, v0
	s_branch .LBB0_219

.LBB0_231:
	v_readlane_b32 s0, v254, 30
	v_readlane_b32 s1, v252, 0
	s_nop 3
	s_cmp_lg_u32 s0, 2
	s_cbranch_scc1 .Lfp_done
	s_cmpk_lg_u32 s1, 0x100
	s_cbranch_scc1 .Lfp_done
	s_lshl_b32 s0, s99, 9
	v_add_u32_e32 v0, s0, v223
	s_mov_b32 s0, 0xb000
	v_cmp_gt_u32_e32 vcc, s0, v0
	s_and_saveexec_b64 s[4:5], vcc
	s_cbranch_execz .Lfp_skip
	v_mov_b32_e32 v1, 0
	s_mov_b32 s0, 0x2c00
	v_cmp_le_u32_e32 vcc, s0, v0
	s_nop 1
	v_addc_co_u32_e32 v1, vcc, 0, v1, vcc
	s_mov_b32 s0, 0x5800
	v_cmp_le_u32_e32 vcc, s0, v0
	s_nop 1
	v_addc_co_u32_e32 v1, vcc, 0, v1, vcc
	s_mov_b32 s0, 0x8400
	v_cmp_le_u32_e32 vcc, s0, v0
	s_nop 1
	v_addc_co_u32_e32 v1, vcc, 0, v1, vcc
	v_mul_u32_u24_e32 v2, 0x2c00, v1
	v_sub_u32_e32 v2, v0, v2
	v_mul_u32_u24_e32 v3, 0x58000, v1
	v_add_lshl_u32 v3, v3, v2, 3
	s_add_u32 s6, s20, 0x1a000000
	s_addc_u32 s7, s21, 0
	v_mov_b32_e32 v4, s6
	v_mov_b32_e32 v5, s7
	v_add_co_u32_e32 v4, vcc, v3, v4
	s_nop 1
	v_addc_co_u32_e32 v5, vcc, 0, v5, vcc
	global_load_dwordx2 v[10:11], v[4:5], off
	v_add_co_u32_e32 v4, vcc, 0x16000, v4
	s_nop 1
	v_addc_co_u32_e32 v5, vcc, 0, v5, vcc
	global_load_dwordx2 v[12:13], v[4:5], off
	v_add_co_u32_e32 v4, vcc, 0x16000, v4
	s_nop 1
	v_addc_co_u32_e32 v5, vcc, 0, v5, vcc
	global_load_dwordx2 v[14:15], v[4:5], off
	v_add_co_u32_e32 v4, vcc, 0x16000, v4
	s_nop 1
	v_addc_co_u32_e32 v5, vcc, 0, v5, vcc
	global_load_dwordx2 v[16:17], v[4:5], off
	v_add_co_u32_e32 v4, vcc, 0x16000, v4
	s_nop 1
	v_addc_co_u32_e32 v5, vcc, 0, v5, vcc
	global_load_dwordx2 v[18:19], v[4:5], off
	v_add_co_u32_e32 v4, vcc, 0x16000, v4
	s_nop 1
	v_addc_co_u32_e32 v5, vcc, 0, v5, vcc
	global_load_dwordx2 v[20:21], v[4:5], off
	v_add_co_u32_e32 v4, vcc, 0x16000, v4
	s_nop 1
	v_addc_co_u32_e32 v5, vcc, 0, v5, vcc
	global_load_dwordx2 v[22:23], v[4:5], off
	v_add_co_u32_e32 v4, vcc, 0x16000, v4
	s_nop 1
	v_addc_co_u32_e32 v5, vcc, 0, v5, vcc
	global_load_dwordx2 v[24:25], v[4:5], off
	v_add_co_u32_e32 v4, vcc, 0x16000, v4
	s_nop 1
	v_addc_co_u32_e32 v5, vcc, 0, v5, vcc
	global_load_dwordx2 v[26:27], v[4:5], off
	v_add_co_u32_e32 v4, vcc, 0x16000, v4
	s_nop 1
	v_addc_co_u32_e32 v5, vcc, 0, v5, vcc
	global_load_dwordx2 v[28:29], v[4:5], off
	v_add_co_u32_e32 v4, vcc, 0x16000, v4
	s_nop 1
	v_addc_co_u32_e32 v5, vcc, 0, v5, vcc
	global_load_dwordx2 v[30:31], v[4:5], off
	v_add_co_u32_e32 v4, vcc, 0x16000, v4
	s_nop 1
	v_addc_co_u32_e32 v5, vcc, 0, v5, vcc
	global_load_dwordx2 v[32:33], v[4:5], off
	v_add_co_u32_e32 v4, vcc, 0x16000, v4
	s_nop 1
	v_addc_co_u32_e32 v5, vcc, 0, v5, vcc
	global_load_dwordx2 v[34:35], v[4:5], off
	v_add_co_u32_e32 v4, vcc, 0x16000, v4
	s_nop 1
	v_addc_co_u32_e32 v5, vcc, 0, v5, vcc
	global_load_dwordx2 v[36:37], v[4:5], off
	v_add_co_u32_e32 v4, vcc, 0x16000, v4
	s_nop 1
	v_addc_co_u32_e32 v5, vcc, 0, v5, vcc
	global_load_dwordx2 v[38:39], v[4:5], off
	v_add_co_u32_e32 v4, vcc, 0x16000, v4
	s_nop 1
	v_addc_co_u32_e32 v5, vcc, 0, v5, vcc
	global_load_dwordx2 v[40:41], v[4:5], off
	v_add_co_u32_e32 v4, vcc, 0x16000, v4
	s_nop 1
	v_addc_co_u32_e32 v5, vcc, 0, v5, vcc
	global_load_dwordx2 v[42:43], v[4:5], off
	v_add_co_u32_e32 v4, vcc, 0x16000, v4
	s_nop 1
	v_addc_co_u32_e32 v5, vcc, 0, v5, vcc
	global_load_dwordx2 v[44:45], v[4:5], off
	v_add_co_u32_e32 v4, vcc, 0x16000, v4
	s_nop 1
	v_addc_co_u32_e32 v5, vcc, 0, v5, vcc
	global_load_dwordx2 v[46:47], v[4:5], off
	v_add_co_u32_e32 v4, vcc, 0x16000, v4
	s_nop 1
	v_addc_co_u32_e32 v5, vcc, 0, v5, vcc
	global_load_dwordx2 v[48:49], v[4:5], off
	v_add_co_u32_e32 v4, vcc, 0x16000, v4
	s_nop 1
	v_addc_co_u32_e32 v5, vcc, 0, v5, vcc
	global_load_dwordx2 v[50:51], v[4:5], off
	v_add_co_u32_e32 v4, vcc, 0x16000, v4
	s_nop 1
	v_addc_co_u32_e32 v5, vcc, 0, v5, vcc
	global_load_dwordx2 v[52:53], v[4:5], off
	v_add_co_u32_e32 v4, vcc, 0x16000, v4
	s_nop 1
	v_addc_co_u32_e32 v5, vcc, 0, v5, vcc
	global_load_dwordx2 v[54:55], v[4:5], off
	v_add_co_u32_e32 v4, vcc, 0x16000, v4
	s_nop 1
	v_addc_co_u32_e32 v5, vcc, 0, v5, vcc
	global_load_dwordx2 v[56:57], v[4:5], off
	v_add_co_u32_e32 v4, vcc, 0x16000, v4
	s_nop 1
	v_addc_co_u32_e32 v5, vcc, 0, v5, vcc
	global_load_dwordx2 v[58:59], v[4:5], off
	v_add_co_u32_e32 v4, vcc, 0x16000, v4
	s_nop 1
	v_addc_co_u32_e32 v5, vcc, 0, v5, vcc
	global_load_dwordx2 v[60:61], v[4:5], off
	v_add_co_u32_e32 v4, vcc, 0x16000, v4
	s_nop 1
	v_addc_co_u32_e32 v5, vcc, 0, v5, vcc
	global_load_dwordx2 v[62:63], v[4:5], off
	v_add_co_u32_e32 v4, vcc, 0x16000, v4
	s_nop 1
	v_addc_co_u32_e32 v5, vcc, 0, v5, vcc
	global_load_dwordx2 v[64:65], v[4:5], off
	v_add_co_u32_e32 v4, vcc, 0x16000, v4
	s_nop 1
	v_addc_co_u32_e32 v5, vcc, 0, v5, vcc
	global_load_dwordx2 v[66:67], v[4:5], off
	v_add_co_u32_e32 v4, vcc, 0x16000, v4
	s_nop 1
	v_addc_co_u32_e32 v5, vcc, 0, v5, vcc
	global_load_dwordx2 v[68:69], v[4:5], off
	v_add_co_u32_e32 v4, vcc, 0x16000, v4
	s_nop 1
	v_addc_co_u32_e32 v5, vcc, 0, v5, vcc
	global_load_dwordx2 v[70:71], v[4:5], off
	v_add_co_u32_e32 v4, vcc, 0x16000, v4
	s_nop 1
	v_addc_co_u32_e32 v5, vcc, 0, v5, vcc
	global_load_dwordx2 v[72:73], v[4:5], off
	s_waitcnt vmcnt(0)
	v_add_f32_e32 v10, v10, v12
	v_add_f32_e32 v11, v11, v13
	v_add_f32_e32 v10, v10, v14
	v_add_f32_e32 v11, v11, v15
	v_add_f32_e32 v10, v10, v16
	v_add_f32_e32 v11, v11, v17
	v_add_f32_e32 v10, v10, v18
	v_add_f32_e32 v11, v11, v19
	v_add_f32_e32 v10, v10, v20
	v_add_f32_e32 v11, v11, v21
	v_add_f32_e32 v10, v10, v22
	v_add_f32_e32 v11, v11, v23
	v_add_f32_e32 v10, v10, v24
	v_add_f32_e32 v11, v11, v25
	v_add_f32_e32 v10, v10, v26
	v_add_f32_e32 v11, v11, v27
	v_add_f32_e32 v10, v10, v28
	v_add_f32_e32 v11, v11, v29
	v_add_f32_e32 v10, v10, v30
	v_add_f32_e32 v11, v11, v31
	v_add_f32_e32 v10, v10, v32
	v_add_f32_e32 v11, v11, v33
	v_add_f32_e32 v10, v10, v34
	v_add_f32_e32 v11, v11, v35
	v_add_f32_e32 v10, v10, v36
	v_add_f32_e32 v11, v11, v37
	v_add_f32_e32 v10, v10, v38
	v_add_f32_e32 v11, v11, v39
	v_add_f32_e32 v10, v10, v40
	v_add_f32_e32 v11, v11, v41
	v_add_f32_e32 v10, v10, v42
	v_add_f32_e32 v11, v11, v43
	v_add_f32_e32 v10, v10, v44
	v_add_f32_e32 v11, v11, v45
	v_add_f32_e32 v10, v10, v46
	v_add_f32_e32 v11, v11, v47
	v_add_f32_e32 v10, v10, v48
	v_add_f32_e32 v11, v11, v49
	v_add_f32_e32 v10, v10, v50
	v_add_f32_e32 v11, v11, v51
	v_add_f32_e32 v10, v10, v52
	v_add_f32_e32 v11, v11, v53
	v_add_f32_e32 v10, v10, v54
	v_add_f32_e32 v11, v11, v55
	v_add_f32_e32 v10, v10, v56
	v_add_f32_e32 v11, v11, v57
	v_add_f32_e32 v10, v10, v58
	v_add_f32_e32 v11, v11, v59
	v_add_f32_e32 v10, v10, v60
	v_add_f32_e32 v11, v11, v61
	v_add_f32_e32 v10, v10, v62
	v_add_f32_e32 v11, v11, v63
	v_add_f32_e32 v10, v10, v64
	v_add_f32_e32 v11, v11, v65
	v_add_f32_e32 v10, v10, v66
	v_add_f32_e32 v11, v11, v67
	v_add_f32_e32 v10, v10, v68
	v_add_f32_e32 v11, v11, v69
	v_add_f32_e32 v10, v10, v70
	v_add_f32_e32 v11, v11, v71
	v_add_f32_e32 v10, v10, v72
	v_add_f32_e32 v11, v11, v73
	v_lshlrev_b32_e32 v6, 15, v1
	v_add_lshl_u32 v6, v6, v2, 2
	s_add_u32 s6, s20, 0x1800a000
	s_addc_u32 s7, s21, 0
	s_add_u32 s8, s20, 0x18015000
	s_addc_u32 s9, s21, 0
	global_store_dword v6, v10, s[6:7]
	global_store_dword v6, v11, s[8:9]
.Lfp_skip:
	s_or_b64 exec, exec, s[4:5]
.Lfp_done:
	s_mov_b64 s[0:1], 0

.LBB0_436:
	v_readfirstlane_b32 s0, v223
	s_ashr_i32 s0, s0, 6
	v_readlane_b32 s1, v253, 22
	s_add_i32 s4, s0, s1
	s_cmp_gt_i32 s4, 0x177ff
	s_cbranch_scc1 .LBB0_459
	v_bfe_u32 v0, v223, 5, 1
	v_lshlrev_b32_e32 v5, 3, v223
	s_lshl_b32 s0, s0, 14
	v_and_b32_e32 v1, 31, v223
	s_waitcnt lgkmcnt(0)
	v_bfe_u32 v3, v223, 3, 3
	v_and_b32_e32 v6, 56, v5
	v_mul_u32_u24_e32 v8, 0x2c00, v0
	v_mul_u32_u24_e32 v9, 0x1400, v0
	s_add_i32 s0, s0, 0
	v_mul_u32_u24_e32 v5, 0x84, v6
	v_lshlrev_b32_e32 v7, 2, v3
	v_or_b32_e32 v8, v8, v1
	v_or_b32_e32 v10, v9, v1
	v_lshl_or_b32 v2, v0, 11, v1
	v_lshl_add_u32 v4, v1, 2, s0
	v_add3_u32 v5, s0, v5, v7
	v_or_b32_e32 v7, 8, v3
	v_or_b32_e32 v12, 16, v3
	v_or_b32_e32 v13, 24, v3
	v_mov_b32_e32 v1, v0
	v_lshlrev_b32_e32 v8, 2, v8
	v_lshlrev_b32_e32 v84, 2, v10
	v_readlane_b32 s36, v252, 2
	v_readlane_b32 s37, v252, 3
	s_nop 3
	s_sub_u32 s36, s36, 0xd0
	s_subb_u32 s37, s37, 0
	s_load_dwordx4 s[40:43], s[36:37], 0x78
	v_lshlrev_b32_e32 v90, 2, v6
	s_waitcnt lgkmcnt(0)
	v_mov_b32_e32 v86, s40
	v_mov_b32_e32 v87, s41
	v_mov_b32_e32 v88, s42
	v_mov_b32_e32 v89, s43
	v_add_co_u32_e32 v86, vcc, v90, v86
	s_nop 1
	v_addc_co_u32_e32 v87, vcc, 0, v87, vcc
	v_add_co_u32_e32 v88, vcc, v90, v88
	s_nop 1
	v_addc_co_u32_e32 v89, vcc, 0, v89, vcc
	s_branch .LBB0_439

.LBB0_446:
	s_and_b64 vcc, exec, s[30:31]
	s_cbranch_vccz .LBB0_450
	v_readlane_b32 s36, v253, 25
	s_mul_i32 s9, s0, 0x5800000
	v_readlane_b32 s38, v253, 27
	s_mul_hi_i32 s8, s0, 0x5800000
	v_readlane_b32 s39, v253, 28
	s_add_u32 s10, s38, s9
	s_addc_u32 s11, s39, s8
	s_add_i32 s8, s5, 0xe400
	s_and_b32 s9, s8, 0xffff
	s_mul_i32 s9, s9, 0xba2f
	s_lshr_b32 s12, s9, 24
	s_mul_i32 s9, s12, 0x160
	s_sub_i32 s13, s8, s9
	s_lshl_b32 s8, s12, 6
	s_lshl_b32 s9, s13, 5
	s_mul_i32 s12, s12, 0x2c0000
	s_add_u32 s10, s10, s12
	s_addc_u32 s11, s11, 0
	s_lshl_b32 s12, s13, 7
	s_and_b32 s12, s12, 0x3ff80
	s_add_u32 s10, s10, s12
	s_addc_u32 s11, s11, 0
	v_mov_b32_e32 v9, v85
	v_readlane_b32 s37, v253, 26
	v_readlane_b32 s40, v253, 29
	v_readlane_b32 s41, v253, 30
	v_readlane_b32 s42, v253, 31
	v_readlane_b32 s43, v253, 32
	v_readlane_b32 s44, v253, 33
	v_readlane_b32 s45, v253, 34
	v_readlane_b32 s46, v253, 35
	v_readlane_b32 s47, v253, 36
	v_readlane_b32 s48, v253, 37
	v_readlane_b32 s49, v253, 38
	v_readlane_b32 s50, v253, 39
	v_readlane_b32 s51, v253, 40
	v_lshl_add_u64 v[10:11], s[10:11], 0, v[8:9]
	s_mov_b32 s10, 1
	s_mov_b32 s11, 0
	s_mov_b32 s12, 32
	s_lshl_b32 s100, s0, 11
	s_add_i32 s100, s100, s8
	s_lshl_b32 s100, s100, 2
	v_add_co_u32_e32 v90, vcc, s100, v86
	s_nop 1
	v_addc_co_u32_e32 v91, vcc, 0, v87, vcc
	v_add_co_u32_e32 v92, vcc, s100, v88
	s_nop 1
	v_addc_co_u32_e32 v93, vcc, 0, v89, vcc
	global_load_dwordx4 v[94:97], v[90:91], off
	global_load_dwordx4 v[98:101], v[90:91], off offset:16
	global_load_dwordx4 v[102:105], v[92:93], off
	global_load_dwordx4 v[106:109], v[92:93], off offset:16
.LBB0_448:
	s_mul_i32 s30, s10, 0x5800
	s_mul_i32 s28, s11, 0x5800
	s_mov_b32 s31, s29
	s_mov_b32 s35, s29
	s_mov_b32 s37, s29
	s_mov_b32 s39, s29
	s_mov_b32 s41, s29
	s_mov_b32 s43, s29
	s_mov_b32 s45, s29
	s_mov_b32 s17, s29
	s_mov_b32 s47, s29
	s_mov_b32 s49, s29
	s_mov_b32 s51, s29
	s_mov_b32 s53, s29
	s_mov_b32 s55, s29
	s_mov_b32 s57, s29
	v_lshl_add_u64 v[14:15], s[28:29], 2, v[10:11]
	s_add_i32 s36, s30, 0xb000
	s_add_i32 s34, s28, 0xb000
	s_add_i32 s40, s30, 0x16000
	s_add_i32 s38, s28, 0x16000
	s_add_i32 s44, s30, 0x21000
	s_add_i32 s42, s28, 0x21000
	s_add_i32 s46, s30, 0x2c000
	s_add_i32 s16, s28, 0x2c000
	s_add_i32 s50, s30, 0x37000
	s_add_i32 s48, s28, 0x37000
	s_add_i32 s54, s30, 0x42000
	s_add_i32 s52, s28, 0x42000
	s_add_i32 s56, s30, 0x4d000
	s_add_i32 s28, s28, 0x4d000
	v_lshl_add_u64 v[16:17], s[30:31], 2, v[10:11]
	v_lshl_add_u64 v[18:19], s[34:35], 2, v[10:11]
	v_lshl_add_u64 v[20:21], s[36:37], 2, v[10:11]
	v_lshl_add_u64 v[22:23], s[38:39], 2, v[10:11]
	v_lshl_add_u64 v[24:25], s[40:41], 2, v[10:11]
	v_lshl_add_u64 v[26:27], s[42:43], 2, v[10:11]
	v_lshl_add_u64 v[28:29], s[44:45], 2, v[10:11]
	v_lshl_add_u64 v[30:31], s[16:17], 2, v[10:11]
	v_lshl_add_u64 v[32:33], s[46:47], 2, v[10:11]
	v_lshl_add_u64 v[34:35], s[48:49], 2, v[10:11]
	v_lshl_add_u64 v[36:37], s[50:51], 2, v[10:11]
	v_lshl_add_u64 v[38:39], s[52:53], 2, v[10:11]
	v_lshl_add_u64 v[40:41], s[54:55], 2, v[10:11]
	v_lshl_add_u64 v[42:43], s[28:29], 2, v[10:11]
	v_lshl_add_u64 v[44:45], s[56:57], 2, v[10:11]
	global_load_dword v9, v[14:15], off
	global_load_dword v46, v[16:17], off
	global_load_dword v47, v[18:19], off
	global_load_dword v48, v[20:21], off
	global_load_dword v49, v[22:23], off
	global_load_dword v50, v[24:25], off
	global_load_dword v51, v[26:27], off
	global_load_dword v52, v[28:29], off
	global_load_dword v53, v[30:31], off
	global_load_dword v54, v[32:33], off
	global_load_dword v55, v[34:35], off
	global_load_dword v56, v[36:37], off
	global_load_dword v57, v[38:39], off
	global_load_dword v58, v[40:41], off
	global_load_dword v59, v[42:43], off
	global_load_dword v60, v[44:45], off
	s_lshl_b32 s13, s10, 1
	s_lshl_b32 s14, s11, 1
	v_or_b32_e32 v16, s13, v1
	v_or_b32_e32 v14, s14, v0
	s_add_i32 s11, s11, 16
	s_add_i32 s10, s10, 16
	s_add_i32 s12, s12, -16
	s_add_i32 s16, s13, 4
	s_add_i32 s17, s14, 4
	s_add_i32 s28, s13, 8
	s_add_i32 s30, s14, 8
	s_add_i32 s31, s13, 12
	s_add_i32 s34, s14, 12
	s_add_i32 s35, s13, 16
	s_add_i32 s36, s14, 16
	s_add_i32 s37, s13, 20
	s_add_i32 s38, s14, 20
	s_add_i32 s39, s13, 24
	s_add_i32 s40, s14, 24
	s_add_i32 s13, s13, 28
	s_add_i32 s41, s14, 28
	v_mad_u64_u32 v[14:15], s[14:15], v14, s27, v[4:5]
	v_mad_u64_u32 v[16:17], s[14:15], v16, s27, v[4:5]
	v_or_b32_e32 v15, s16, v1
	v_or_b32_e32 v17, s17, v0
	v_or_b32_e32 v24, s28, v1
	v_or_b32_e32 v22, s30, v0
	v_or_b32_e32 v28, s31, v1
	v_or_b32_e32 v26, s34, v0
	v_or_b32_e32 v32, s35, v1
	v_or_b32_e32 v30, s36, v0
	v_or_b32_e32 v36, s37, v1
	v_or_b32_e32 v34, s38, v0
	v_or_b32_e32 v40, s39, v1
	v_or_b32_e32 v38, s40, v0
	v_or_b32_e32 v44, s13, v1
	v_or_b32_e32 v42, s41, v0
	s_cmp_lg_u32 s12, 0
	v_mad_u64_u32 v[18:19], s[14:15], v17, s27, v[4:5]
	v_mad_u64_u32 v[20:21], s[14:15], v15, s27, v[4:5]
	v_mad_u64_u32 v[22:23], s[14:15], v22, s27, v[4:5]
	v_mad_u64_u32 v[24:25], s[14:15], v24, s27, v[4:5]
	v_mad_u64_u32 v[26:27], s[14:15], v26, s27, v[4:5]
	v_mad_u64_u32 v[28:29], s[14:15], v28, s27, v[4:5]
	v_mad_u64_u32 v[30:31], s[14:15], v30, s27, v[4:5]
	v_mad_u64_u32 v[32:33], s[14:15], v32, s27, v[4:5]
	v_mad_u64_u32 v[34:35], s[14:15], v34, s27, v[4:5]
	v_mad_u64_u32 v[36:37], s[14:15], v36, s27, v[4:5]
	v_mad_u64_u32 v[38:39], s[14:15], v38, s27, v[4:5]
	v_mad_u64_u32 v[40:41], s[14:15], v40, s27, v[4:5]
	v_mad_u64_u32 v[42:43], s[14:15], v42, s27, v[4:5]
	v_mad_u64_u32 v[44:45], s[14:15], v44, s27, v[4:5]
	s_waitcnt vmcnt(0)
	ds_write_b32 v14, v9
	ds_write_b32 v16, v46
	ds_write_b32 v18, v47
	ds_write_b32 v20, v48
	ds_write_b32 v22, v49
	ds_write_b32 v24, v50
	ds_write_b32 v26, v51
	ds_write_b32 v28, v52
	ds_write_b32 v30, v53
	ds_write_b32 v32, v54
	ds_write_b32 v34, v55
	ds_write_b32 v36, v56
	ds_write_b32 v38, v57
	ds_write_b32 v40, v58
	ds_write_b32 v42, v59
	ds_write_b32 v44, v60
	s_cbranch_scc1 .LBB0_448
	v_readlane_b32 s10, v253, 44
	s_waitcnt lgkmcnt(0)
	s_add_u32 s7, s10, s7
	v_readlane_b32 s10, v253, 45
	ds_read2_b32 v[18:19], v5 offset0:33 offset1:41
	ds_read2_b32 v[20:21], v5 offset1:8
	ds_read2_b32 v[22:23], v5 offset0:66 offset1:74
	ds_read2_b32 v[24:25], v5 offset0:99 offset1:107
	ds_read2_b32 v[26:27], v5 offset0:132 offset1:140
	ds_read2_b32 v[28:29], v5 offset0:165 offset1:173
	ds_read2_b32 v[30:31], v5 offset0:198 offset1:206
	ds_read2_b32 v[32:33], v5 offset0:231 offset1:239
	s_addc_u32 s10, s10, s6
	s_and_b32 s9, 0xffff, s9
	s_lshl_b32 s6, s8, 1
	s_add_u32 s6, s7, s6
	s_addc_u32 s7, s10, 0
	v_lshlrev_b32_e32 v10, 1, v6
	v_mov_b32_e32 v11, v85
	v_or_b32_e32 v9, s9, v3
	v_lshl_add_u64 v[10:11], s[6:7], 0, v[10:11]
	v_lshlrev_b32_e32 v34, 12, v9
	v_mov_b32_e32 v35, v85
	s_waitcnt lgkmcnt(6)
	v_cvt_pk_bf16_f32 v14, v20, v18
	s_waitcnt lgkmcnt(4)
	v_cvt_pk_bf16_f32 v15, v22, v24
	s_waitcnt lgkmcnt(2)
	v_cvt_pk_bf16_f32 v16, v26, v28
	s_waitcnt lgkmcnt(0)
	v_cvt_pk_bf16_f32 v17, v30, v32
	v_lshl_add_u64 v[34:35], v[10:11], 0, v[34:35]
	global_store_dwordx4 v[34:35], v[14:17], off
	v_lshlrev_b32_e32 v110, 16, v14
	v_and_b32_e32 v111, 0xffff0000, v14
	v_lshlrev_b32_e32 v112, 16, v15
	v_and_b32_e32 v113, 0xffff0000, v15
	v_lshlrev_b32_e32 v114, 16, v16
	v_and_b32_e32 v115, 0xffff0000, v16
	v_lshlrev_b32_e32 v116, 16, v17
	v_and_b32_e32 v117, 0xffff0000, v17
	v_mul_f32_e32 v118, v94, v110
	v_mul_f32_e32 v119, v102, v110
	v_fmac_f32_e32 v118, v95, v111
	v_fmac_f32_e32 v119, v103, v111
	v_fmac_f32_e32 v118, v96, v112
	v_fmac_f32_e32 v119, v104, v112
	v_fmac_f32_e32 v118, v97, v113
	v_fmac_f32_e32 v119, v105, v113
	v_fmac_f32_e32 v118, v98, v114
	v_fmac_f32_e32 v119, v106, v114
	v_fmac_f32_e32 v118, v99, v115
	v_fmac_f32_e32 v119, v107, v115
	v_fmac_f32_e32 v118, v100, v116
	v_fmac_f32_e32 v119, v108, v116
	v_fmac_f32_e32 v118, v101, v117
	v_fmac_f32_e32 v119, v109, v117
	v_or_b32_e32 v9, s9, v7
	v_lshlrev_b32_e32 v18, 12, v9
	v_cvt_pk_bf16_f32 v14, v21, v19
	v_cvt_pk_bf16_f32 v15, v23, v25
	v_cvt_pk_bf16_f32 v16, v27, v29
	v_cvt_pk_bf16_f32 v17, v31, v33
	ds_read2_b32 v[20:21], v5 offset0:49 offset1:57
	ds_read2_b32 v[22:23], v5 offset0:16 offset1:24
	ds_read2_b32 v[24:25], v5 offset0:82 offset1:90
	ds_read2_b32 v[26:27], v5 offset0:115 offset1:123
	ds_read2_b32 v[28:29], v5 offset0:148 offset1:156
	ds_read2_b32 v[30:31], v5 offset0:181 offset1:189
	ds_read2_b32 v[32:33], v5 offset0:214 offset1:222
	ds_read2_b32 v[34:35], v5 offset0:247 offset1:255
	v_mov_b32_e32 v19, v85
	v_lshl_add_u64 v[18:19], v[10:11], 0, v[18:19]
	v_or_b32_e32 v9, s9, v12
	global_store_dwordx4 v[18:19], v[14:17], off
	v_lshlrev_b32_e32 v110, 16, v14
	v_and_b32_e32 v111, 0xffff0000, v14
	v_lshlrev_b32_e32 v112, 16, v15
	v_and_b32_e32 v113, 0xffff0000, v15
	v_lshlrev_b32_e32 v114, 16, v16
	v_and_b32_e32 v115, 0xffff0000, v16
	v_lshlrev_b32_e32 v116, 16, v17
	v_and_b32_e32 v117, 0xffff0000, v17
	v_mul_f32_e32 v120, v94, v110
	v_mul_f32_e32 v121, v102, v110
	v_fmac_f32_e32 v120, v95, v111
	v_fmac_f32_e32 v121, v103, v111
	v_fmac_f32_e32 v120, v96, v112
	v_fmac_f32_e32 v121, v104, v112
	v_fmac_f32_e32 v120, v97, v113
	v_fmac_f32_e32 v121, v105, v113
	v_fmac_f32_e32 v120, v98, v114
	v_fmac_f32_e32 v121, v106, v114
	v_fmac_f32_e32 v120, v99, v115
	v_fmac_f32_e32 v121, v107, v115
	v_fmac_f32_e32 v120, v100, v116
	v_fmac_f32_e32 v121, v108, v116
	v_fmac_f32_e32 v120, v101, v117
	v_fmac_f32_e32 v121, v109, v117
	v_lshlrev_b32_e32 v18, 12, v9
	v_mov_b32_e32 v19, v85
	s_waitcnt lgkmcnt(6)
	v_cvt_pk_bf16_f32 v14, v22, v20
	s_waitcnt lgkmcnt(4)
	v_cvt_pk_bf16_f32 v15, v24, v26
	s_waitcnt lgkmcnt(2)
	v_cvt_pk_bf16_f32 v16, v28, v30
	s_waitcnt lgkmcnt(0)
	v_cvt_pk_bf16_f32 v17, v32, v34
	v_lshl_add_u64 v[18:19], v[10:11], 0, v[18:19]
	v_or_b32_e32 v9, s9, v13
	global_store_dwordx4 v[18:19], v[14:17], off
	v_lshlrev_b32_e32 v110, 16, v14
	v_and_b32_e32 v111, 0xffff0000, v14
	v_lshlrev_b32_e32 v112, 16, v15
	v_and_b32_e32 v113, 0xffff0000, v15
	v_lshlrev_b32_e32 v114, 16, v16
	v_and_b32_e32 v115, 0xffff0000, v16
	v_lshlrev_b32_e32 v116, 16, v17
	v_and_b32_e32 v117, 0xffff0000, v17
	v_mul_f32_e32 v122, v94, v110
	v_mul_f32_e32 v123, v102, v110
	v_fmac_f32_e32 v122, v95, v111
	v_fmac_f32_e32 v123, v103, v111
	v_fmac_f32_e32 v122, v96, v112
	v_fmac_f32_e32 v123, v104, v112
	v_fmac_f32_e32 v122, v97, v113
	v_fmac_f32_e32 v123, v105, v113
	v_fmac_f32_e32 v122, v98, v114
	v_fmac_f32_e32 v123, v106, v114
	v_fmac_f32_e32 v122, v99, v115
	v_fmac_f32_e32 v123, v107, v115
	v_fmac_f32_e32 v122, v100, v116
	v_fmac_f32_e32 v123, v108, v116
	v_fmac_f32_e32 v122, v101, v117
	v_fmac_f32_e32 v123, v109, v117
	v_lshlrev_b32_e32 v18, 12, v9
	v_mov_b32_e32 v19, v85
	v_cvt_pk_bf16_f32 v14, v23, v21
	v_cvt_pk_bf16_f32 v15, v25, v27
	v_cvt_pk_bf16_f32 v16, v29, v31
	v_cvt_pk_bf16_f32 v17, v33, v35
	v_lshl_add_u64 v[10:11], v[10:11], 0, v[18:19]
	global_store_dwordx4 v[10:11], v[14:17], off
	v_lshlrev_b32_e32 v110, 16, v14
	v_and_b32_e32 v111, 0xffff0000, v14
	v_lshlrev_b32_e32 v112, 16, v15
	v_and_b32_e32 v113, 0xffff0000, v15
	v_lshlrev_b32_e32 v114, 16, v16
	v_and_b32_e32 v115, 0xffff0000, v16
	v_lshlrev_b32_e32 v116, 16, v17
	v_and_b32_e32 v117, 0xffff0000, v17
	v_mul_f32_e32 v124, v94, v110
	v_mul_f32_e32 v125, v102, v110
	v_fmac_f32_e32 v124, v95, v111
	v_fmac_f32_e32 v125, v103, v111
	v_fmac_f32_e32 v124, v96, v112
	v_fmac_f32_e32 v125, v104, v112
	v_fmac_f32_e32 v124, v97, v113
	v_fmac_f32_e32 v125, v105, v113
	v_fmac_f32_e32 v124, v98, v114
	v_fmac_f32_e32 v125, v106, v114
	v_fmac_f32_e32 v124, v99, v115
	v_fmac_f32_e32 v125, v107, v115
	v_fmac_f32_e32 v124, v100, v116
	v_fmac_f32_e32 v125, v108, v116
	v_fmac_f32_e32 v124, v101, v117
	v_fmac_f32_e32 v125, v109, v117
	v_add_f32_dpp v118, v118, v118 quad_perm:[1,0,3,2] row_mask:0xf bank_mask:0xf
	v_add_f32_dpp v119, v119, v119 quad_perm:[1,0,3,2] row_mask:0xf bank_mask:0xf
	v_add_f32_dpp v120, v120, v120 quad_perm:[1,0,3,2] row_mask:0xf bank_mask:0xf
	v_add_f32_dpp v121, v121, v121 quad_perm:[1,0,3,2] row_mask:0xf bank_mask:0xf
	v_add_f32_dpp v122, v122, v122 quad_perm:[1,0,3,2] row_mask:0xf bank_mask:0xf
	v_add_f32_dpp v123, v123, v123 quad_perm:[1,0,3,2] row_mask:0xf bank_mask:0xf
	v_add_f32_dpp v124, v124, v124 quad_perm:[1,0,3,2] row_mask:0xf bank_mask:0xf
	v_add_f32_dpp v125, v125, v125 quad_perm:[1,0,3,2] row_mask:0xf bank_mask:0xf
	v_add_f32_dpp v118, v118, v118 quad_perm:[2,3,0,1] row_mask:0xf bank_mask:0xf
	v_add_f32_dpp v119, v119, v119 quad_perm:[2,3,0,1] row_mask:0xf bank_mask:0xf
	v_add_f32_dpp v120, v120, v120 quad_perm:[2,3,0,1] row_mask:0xf bank_mask:0xf
	v_add_f32_dpp v121, v121, v121 quad_perm:[2,3,0,1] row_mask:0xf bank_mask:0xf
	v_add_f32_dpp v122, v122, v122 quad_perm:[2,3,0,1] row_mask:0xf bank_mask:0xf
	v_add_f32_dpp v123, v123, v123 quad_perm:[2,3,0,1] row_mask:0xf bank_mask:0xf
	v_add_f32_dpp v124, v124, v124 quad_perm:[2,3,0,1] row_mask:0xf bank_mask:0xf
	v_add_f32_dpp v125, v125, v125 quad_perm:[2,3,0,1] row_mask:0xf bank_mask:0xf
	v_add_f32_dpp v118, v118, v118 row_half_mirror row_mask:0xf bank_mask:0xf
	v_add_f32_dpp v119, v119, v119 row_half_mirror row_mask:0xf bank_mask:0xf
	v_add_f32_dpp v120, v120, v120 row_half_mirror row_mask:0xf bank_mask:0xf
	v_add_f32_dpp v121, v121, v121 row_half_mirror row_mask:0xf bank_mask:0xf
	v_add_f32_dpp v122, v122, v122 row_half_mirror row_mask:0xf bank_mask:0xf
	v_add_f32_dpp v123, v123, v123 row_half_mirror row_mask:0xf bank_mask:0xf
	v_add_f32_dpp v124, v124, v124 row_half_mirror row_mask:0xf bank_mask:0xf
	v_add_f32_dpp v125, v125, v125 row_half_mirror row_mask:0xf bank_mask:0xf
	v_cmp_eq_u32_e32 vcc, 0, v6
	s_and_saveexec_b64 s[36:37], vcc
	s_lshl_b32 s100, s0, 5
	s_lshr_b32 s101, s8, 6
	s_add_i32 s100, s100, s101
	s_mul_i32 s100, s100, 0x2c00
	s_and_b32 s101, s9, 0xffff
	s_add_i32 s100, s100, s101
	s_lshl_b32 s100, s100, 3
	s_add_u32 s38, s20, 0x1a000000
	s_addc_u32 s39, s21, 0
	v_lshlrev_b32_e32 v126, 3, v3
	v_add_u32_e32 v126, s100, v126
	global_store_dwordx2 v126, v[118:119], s[38:39]
	global_store_dwordx2 v126, v[120:121], s[38:39] offset:64
	global_store_dwordx2 v126, v[122:123], s[38:39] offset:128
	global_store_dwordx2 v126, v[124:125], s[38:39] offset:192
	s_or_b64 exec, exec, s[36:37]
	s_waitcnt lgkmcnt(0)
	v_readlane_b32 s50, v254, 61
	v_readlane_b32 s12, v255, 0
	s_movk_i32 s17, 0x1000
	v_readlane_b32 s51, v254, 62
	v_readlane_b32 s13, v255, 1
